# hand-scheduled attention body extended to near and diagonal full tiles (bias/mask stage between QK and max)
# speedup vs baseline: 1.0038x; 1.0038x over previous
; #define LAS __attribute__((address_space(3)))
; #define ATT_LOAD(t) do { const int tw_ = DIFF ? (t) : ((t) & 3); const bf16* Kt_ = Kh + (kvrow0 + (size_t)tw_ * 64) * kvpitch; const bf16* Vt_ = Vh + (kvrow0 + (size_t)tw_ * 64) * kvpitch; \
;         _Pragma("unroll") for (int i_ = 0; i_ < 2; ++i_) { kreg[i_] = *(const bf16x8*)(Kt_ + loff + 32 * i_ * kvpitch); vreg[i_] = *(const bf16x8*)(Vt_ + loff + 32 * i_ * kvpitch); } } while (0)
; #define ATT_STORE(ks, vs) do { _Pragma("unroll") for (int i_ = 0; i_ < 2; ++i_) { const int kv_ = skv0 + 32 * i_; \
;         *(LAS bf16x8*)(L + (ks) * KSLOT + (kv_ * KP + scol) * 2) = kreg[i_]; *(LAS bf16x8*)(L + 2 * KSLOT + (vs) * VSLOT + (kv_ * VP + scol) * 2) = vreg[i_]; } } while (0)
; template <bool DIFF> DI void attn_unit(LAS unsigned char* L, const bf16* Qh, int qpitch, const bf16* Kh, const bf16* Vh, int kvpitch, bf16* Oh, int opitch, ...
;     ...
;     for (int t = 0; t < NT; ++t) {
;         const int cur = t & 1, vnext = (vcur == 2) ? 0 : vcur + 1;
;         if (t + 1 < NT) ATT_STORE(cur ^ 1, vnext);
;         if (t + 2 < NT) ATT_LOAD(t + 2);
;         const LAS unsigned char* Kc = L + cur * KSLOT + koff;
;         const bool act0 = !DIFF || (64 * t <= qlast), act1 = !DIFF || (64 * t + 32 <= qlast);
;         if (stag && pa0) att_pv(L + voff + vprev * VSLOT, pf, y, pa1);
;         if (act0) att_qk_softmax<DIFF, ND0>(Kc, qf, tbl, t, qbase, r, h_, act1, m_run, l_run, negm, y, pf);
.LBB0_191:
	s_add_i32 s96, s87, -1
	s_and_b32 s8, s96, 1
	s_add_i32 s36, s94, 1
	s_cmp_lg_u32 s94, 2
	s_mov_b32 s95, s94
	s_cselect_b32 s94, s36, 0
	s_cmpk_gt_i32 s84, 0x7f
	s_cbranch_scc1 .Lfast
	s_cmp_lt_i32 s25, s1
	s_cbranch_scc0 .Lhead_gen
	s_cmp_ge_u32 s87, s93
	s_cbranch_scc1 .Lhead_gen
	s_cmp_lt_u32 s96, s86
	s_cbranch_scc1 .Lfast

; #define LAS __attribute__((address_space(3)))
; DI int crow(int i, int h) { return (i & 3) + 8 * (i >> 2) + 4 * h; }
; #define ATT_LOAD(t) do { const int tw_ = DIFF ? (t) : ((t) & 3); const bf16* Kt_ = Kh + (kvrow0 + (size_t)tw_ * 64) * kvpitch; const bf16* Vt_ = Vh + (kvrow0 + (size_t)tw_ * 64) * kvpitch; \
;         _Pragma("unroll") for (int i_ = 0; i_ < 2; ++i_) { kreg[i_] = *(const bf16x8*)(Kt_ + loff + 32 * i_ * kvpitch); vreg[i_] = *(const bf16x8*)(Vt_ + loff + 32 * i_ * kvpitch); } } while (0)
; #define ATT_STORE(ks, vs) do { _Pragma("unroll") for (int i_ = 0; i_ < 2; ++i_) { const int kv_ = skv0 + 32 * i_; \
;         *(LAS bf16x8*)(L + (ks) * KSLOT + (kv_ * KP + scol) * 2) = kreg[i_]; *(LAS bf16x8*)(L + 2 * KSLOT + (vs) * VSLOT + (kv_ * VP + scol) * 2) = vreg[i_]; } } while (0)
; template <bool DIFF, int ND0> DI void att_qk_softmax(const LAS unsigned char* Kc, const bf16x8 (&qf)[ND0], const LAS float* tbl, int t, int qbase, int r, int h_, bool act1, ...
;     ...
;     for (int sub = 0; sub < 2; ++sub) {
;         p[sub] = negm;
;         if (sub == 0 || act1) {
; #pragma unroll
;             for (int d0 = 0; d0 < ND0; ++d0) { const bf16x8 kf = *(const LAS bf16x8*)(Kc + (32 * sub * ATT_KP + 16 * d0) * 2);
;                 p[sub] = __builtin_amdgcn_mfma_f32_32x32x16_bf16(kf, qf[d0], p[sub], 0, 0, 0); }
;         }
;     }
;     const bool far = !DIFF || (qbase - (64 * t + 63) >= 128);
;     if (!far) {
;         const int qpos = qbase + r;
; #pragma unroll
;         for (int sub = 0; sub < 2; ++sub)
; #pragma unroll
;             for (int i = 0; i < 16; ++i) { const int dist = qpos - (64 * t + 32 * sub + crow(i, h_));
;                 const int idx = dist < 0 ? 0 : (dist > 255 ? 255 : dist); float s = p[sub][i] + tbl[idx]; s = dist >= 0 ? s : -INFINITY;
;                 if (sub == 1 && !act1) s = -INFINITY;
;                 p[sub][i] = s; }
;     }
; template <bool DIFF> DI void attn_unit(LAS unsigned char* L, const bf16* Qh, int qpitch, const bf16* Kh, const bf16* Vh, int kvpitch, bf16* Oh, int opitch, ...
;     ...
;         if (t + 1 < NT) ATT_STORE(cur ^ 1, vnext);
;         if (t + 2 < NT) ATT_LOAD(t + 2);
.Lfast:
	s_mulk_i32 s8, 0x4400
	v_add_u32_e32 v221, s8, v216
	ds_read_b128 v[96:99], v221
	ds_read_b128 v[100:103], v221 offset:32
	ds_read_b128 v[104:107], v221 offset:64
	ds_read_b128 v[108:111], v221 offset:96
	ds_read_b128 v[222:225], v221 offset:8704
	ds_read_b128 v[226:229], v221 offset:8736
	ds_read_b128 v[230:233], v221 offset:8768
	ds_read_b128 v[234:237], v221 offset:8800
	s_and_b32 s36, s96, 1
	s_xor_b32 s36, s36, 1
	s_mulk_i32 s36, 0x4400
	s_mul_i32 s85, s94, 0x5000
	s_waitcnt lgkmcnt(0)
	v_mfma_f32_32x32x16_bf16 v[80:95], v[96:99], v[112:115], v[64:79]
	v_add_u32_e32 v239, s36, v210
	s_waitcnt vmcnt(3)
	ds_write_b128 v239, v[128:131]
	v_mfma_f32_32x32x16_bf16 v[80:95], v[100:103], v[116:119], v[80:95]
	v_add_u32_e32 v239, s85, v211
	s_waitcnt vmcnt(2)
	ds_write_b128 v239, v[132:135] offset:34816
	v_mfma_f32_32x32x16_bf16 v[80:95], v[104:107], v[120:123], v[80:95]
	v_add_u32_e32 v239, s36, v212
	s_waitcnt vmcnt(1)
	ds_write_b128 v239, v[136:139]
	v_mfma_f32_32x32x16_bf16 v[80:95], v[108:111], v[124:127], v[80:95]
	v_add_u32_e32 v239, s85, v213
	s_waitcnt vmcnt(0)
	ds_write_b128 v239, v[140:143] offset:34816
	v_mfma_f32_32x32x16_bf16 v[96:111], v[222:225], v[112:115], v[64:79]
	v_lshl_add_u64 v[240:241], v[198:199], 0, s[10:11]
	v_add_co_u32_e32 v242, vcc, 0x13060000, v240
	s_nop 1
	v_addc_co_u32_e32 v243, vcc, 0, v241, vcc
	v_add_co_u32_e32 v244, vcc, 0x15060000, v240
	s_nop 1
	v_addc_co_u32_e32 v245, vcc, 0, v241, vcc
	v_mfma_f32_32x32x16_bf16 v[96:111], v[226:229], v[116:119], v[96:111]
	global_load_dwordx4 v[128:131], v[242:243], off
	global_load_dwordx4 v[132:135], v[244:245], off
	v_add_co_u32_e32 v242, vcc, 0x13070000, v240
	s_nop 1
	v_addc_co_u32_e32 v243, vcc, 0, v241, vcc
	v_add_co_u32_e32 v240, vcc, 0x15070000, v240
	s_nop 1
	v_addc_co_u32_e32 v241, vcc, 0, v241, vcc
	v_mfma_f32_32x32x16_bf16 v[96:111], v[230:233], v[120:123], v[96:111]
	global_load_dwordx4 v[136:139], v[242:243], off
	global_load_dwordx4 v[140:143], v[240:241], off
	v_mfma_f32_32x32x16_bf16 v[96:111], v[234:237], v[124:127], v[96:111]
	s_cmpk_gt_i32 s84, 0x7f
	s_cbranch_scc1 .Lfast_nb
	v_add_u32_e32 v221, s84, v219
	v_lshl_add_u32 v238, v221, 2, s89
	v_add_u32_e32 v239, 63, v221
	ds_read2_b32 v[222:223], v238 offset0:63 offset1:62
	ds_read2_b32 v[224:225], v238 offset0:61 offset1:60
	ds_read2_b32 v[226:227], v238 offset0:55 offset1:54
	ds_read2_b32 v[228:229], v238 offset0:53 offset1:52
	ds_read2_b32 v[230:231], v238 offset0:47 offset1:46
	ds_read2_b32 v[232:233], v238 offset0:45 offset1:44
	ds_read2_b32 v[234:235], v238 offset0:39 offset1:38
	ds_read2_b32 v[236:237], v238 offset0:37 offset1:36
	s_waitcnt lgkmcnt(0)
	s_nop 3
	v_add_f32_e32 v80, v80, v222
	v_add_f32_e32 v81, v81, v223
	v_add_f32_e32 v82, v82, v224
	v_add_f32_e32 v83, v83, v225
	v_add_f32_e32 v84, v84, v226
	v_add_f32_e32 v85, v85, v227
	v_add_f32_e32 v86, v86, v228
	v_add_f32_e32 v87, v87, v229
	v_add_f32_e32 v88, v88, v230
	v_add_f32_e32 v89, v89, v231
	v_add_f32_e32 v90, v90, v232
	v_add_f32_e32 v91, v91, v233
	v_add_f32_e32 v92, v92, v234
	v_add_f32_e32 v93, v93, v235
	v_add_f32_e32 v94, v94, v236
	v_add_f32_e32 v95, v95, v237
	ds_read2_b32 v[222:223], v238 offset0:31 offset1:30
	ds_read2_b32 v[224:225], v238 offset0:29 offset1:28
	ds_read2_b32 v[226:227], v238 offset0:23 offset1:22
	ds_read2_b32 v[228:229], v238 offset0:21 offset1:20
	ds_read2_b32 v[230:231], v238 offset0:15 offset1:14
	ds_read2_b32 v[232:233], v238 offset0:13 offset1:12
	ds_read2_b32 v[234:235], v238 offset0:7 offset1:6
	ds_read2_b32 v[236:237], v238 offset0:5 offset1:4
	s_cmp_lt_i32 s84, -32
	s_cbranch_scc0 .Lfast_nm0
	v_cmp_le_i32_e32 vcc, 0, v239
	v_cmp_le_i32_e64 s[8:9], 1, v239
	s_nop 0
	v_cndmask_b32_e32 v80, v207, v80, vcc
	v_cndmask_b32_e64 v81, v207, v81, s[8:9]
	v_cmp_le_i32_e32 vcc, 2, v239
	v_cmp_le_i32_e64 s[8:9], 3, v239
	s_nop 0
	v_cndmask_b32_e32 v82, v207, v82, vcc
	v_cndmask_b32_e64 v83, v207, v83, s[8:9]
	v_cmp_le_i32_e32 vcc, 8, v239
	v_cmp_le_i32_e64 s[8:9], 9, v239
	s_nop 0
	v_cndmask_b32_e32 v84, v207, v84, vcc
	v_cndmask_b32_e64 v85, v207, v85, s[8:9]
	v_cmp_le_i32_e32 vcc, 10, v239
	v_cmp_le_i32_e64 s[8:9], 11, v239
	s_nop 0
	v_cndmask_b32_e32 v86, v207, v86, vcc
	v_cndmask_b32_e64 v87, v207, v87, s[8:9]
	v_cmp_le_i32_e32 vcc, 16, v239
	v_cmp_le_i32_e64 s[8:9], 17, v239
	s_nop 0
	v_cndmask_b32_e32 v88, v207, v88, vcc
	v_cndmask_b32_e64 v89, v207, v89, s[8:9]
	v_cmp_le_i32_e32 vcc, 18, v239
	v_cmp_le_i32_e64 s[8:9], 19, v239
	s_nop 0
	v_cndmask_b32_e32 v90, v207, v90, vcc
	v_cndmask_b32_e64 v91, v207, v91, s[8:9]
	v_cmp_le_i32_e32 vcc, 24, v239
	v_cmp_le_i32_e64 s[8:9], 25, v239
	s_nop 0
	v_cndmask_b32_e32 v92, v207, v92, vcc
	v_cndmask_b32_e64 v93, v207, v93, s[8:9]
	v_cmp_le_i32_e32 vcc, 26, v239
	v_cmp_le_i32_e64 s[8:9], 27, v239
	s_nop 0
	v_cndmask_b32_e32 v94, v207, v94, vcc
	v_cndmask_b32_e64 v95, v207, v95, s[8:9]

; template <bool DIFF, int ND0> DI void att_qk_softmax(const LAS unsigned char* Kc, const bf16x8 (&qf)[ND0], const LAS float* tbl, int t, int qbase, int r, int h_, bool act1, ...
;     ...
;     float mx = -INFINITY;
; #pragma unroll
;     for (int sub = 0; sub < 2; ++sub)
; #pragma unroll
;         for (int i = 0; i < 16; ++i) mx = fmaxf(mx, p[sub][i]);
;     mx = xmax32(mx);
;     if (t == 0 || __any(mx > 8.f)) {
;         const float dl = (t == 0) ? mx : fmaxf(mx, 0.f), alpha = __builtin_amdgcn_exp2f(-dl);
;         m_run += dl; l_run *= alpha;
; #pragma unroll
;         for (int i = 0; i < 16; ++i) { negm[i] = -m_run; p[0][i] -= dl; p[1][i] -= dl; }
; #pragma unroll
;         for (int d0 = 0; d0 < 4; ++d0)
; #pragma unroll
;             for (int i = 0; i < 16; ++i) y[d0][i] *= alpha;
;     }
;     float rs = 0.f;
; #pragma unroll
;     for (int sub = 0; sub < 2; ++sub)
; #pragma unroll
;         for (int i = 0; i < 16; ++i) { const float e = __builtin_amdgcn_exp2f(p[sub][i]); p[sub][i] = e; rs += e; }
;     l_run += rs;
; #pragma unroll
;     for (int sub = 0; sub < 2; ++sub)
; #pragma unroll
;         for (int s = 0; s < 2; ++s) { u32x4 pw; pw.x = pk2(p[sub][8 * s], p[sub][8 * s + 1]); pw.y = pk2(p[sub][8 * s + 2], p[sub][8 * s + 3]); pw.z = pk2(p[sub][8 * s + 4], p[sub][8 * s + 5]); pw.w = pk2(p[sub][8 * s + 6], p[sub][8 * s + 7]);
;             pf[sub][s] = __builtin_bit_cast(bf16x8, pw); }
; }
; DI void att_pv(const LAS unsigned char* Vc, const bf16x8 (&pf)[2][2], f32x16 (&y)[4], bool act1) {
; #pragma unroll
;     for (int sub = 0; sub < 2; ++sub) {
;         if (sub == 0 || act1) {
; #pragma unroll
;             for (int s = 0; s < 2; ++s) {
;             __builtin_amdgcn_sched_barrier(0);
; #pragma unroll
;                 for (int d0 = 0; d0 < 4; ++d0) { const LAS unsigned char* vp = Vc + ((32 * sub + 16 * s) * ATT_VP + 32 * d0) * 2;
;                     const s16x4 lo = __builtin_bit_cast(s16x4, __builtin_amdgcn_ds_read_tr16_b64_v4i16((LAS v4i16_t*)vp));
;                     const s16x4 hi = __builtin_bit_cast(s16x4, __builtin_amdgcn_ds_read_tr16_b64_v4i16((LAS v4i16_t*)(vp + 8 * ATT_VP * 2)));
;                     const bf16x8 vf = __builtin_shufflevector(lo, hi, 0, 1, 2, 3, 4, 5, 6, 7);
;                     y[d0] = __builtin_amdgcn_mfma_f32_32x32x16_bf16(vf, pf[sub][s], y[d0], 0, 0, 0); }
;             }
;         }
;     }
.Lfast_nb:
	s_mul_i32 s8, s95, 0x5000
	v_add_u32_e32 v238, s8, v217
	ds_read_b64_tr_b16 v[240:241], v238 offset:34816
	ds_read_b64_tr_b16 v[242:243], v238 offset:37376
	ds_read_b64_tr_b16 v[244:245], v238 offset:34880
	ds_read_b64_tr_b16 v[246:247], v238 offset:37440
	ds_read_b64_tr_b16 v[248:249], v238 offset:34944
	ds_read_b64_tr_b16 v[250:251], v238 offset:37504
	s_nop 4
	v_max3_f32 v208, v80, s3, v81
	v_max3_f32 v208, v208, v82, v83
	v_max3_f32 v208, v208, v84, v85
	v_max3_f32 v208, v208, v86, v87
	v_max3_f32 v208, v208, v88, v89
	v_max3_f32 v208, v208, v90, v91
	v_max3_f32 v208, v208, v92, v93
	v_max3_f32 v208, v208, v94, v95
	v_max3_f32 v208, v208, v96, v97
	v_max3_f32 v208, v208, v98, v99
	v_max3_f32 v208, v208, v100, v101
	v_max3_f32 v208, v208, v102, v103
	v_max3_f32 v208, v208, v104, v105
	v_max3_f32 v208, v208, v106, v107
	v_max3_f32 v208, v208, v108, v109
	v_max3_f32 v208, v208, v110, v111
	v_mov_b32_e32 v221, v208
	s_nop 1
	v_permlane32_swap_b32_e32 v208, v221
	v_max_f32_e32 v221, v221, v221
	v_max_f32_e32 v208, v208, v208
	v_max_f32_e32 v221, v208, v221
	v_cmp_lt_f32_e32 vcc, s92, v221
	s_cbranch_vccnz .Lfast_resc
	v_exp_f32_e32 v80, v80
	v_exp_f32_e32 v81, v81
	v_exp_f32_e32 v82, v82
	v_exp_f32_e32 v83, v83
	v_add_f32_e32 v208, 0, v80
	v_exp_f32_e32 v84, v84
	v_add_f32_e32 v208, v81, v208
	v_exp_f32_e32 v85, v85
	v_add_f32_e32 v208, v82, v208
	v_exp_f32_e32 v86, v86
	v_add_f32_e32 v208, v83, v208
	v_exp_f32_e32 v87, v87
	v_add_f32_e32 v208, v84, v208
	v_exp_f32_e32 v88, v88
	v_add_f32_e32 v208, v85, v208
	v_exp_f32_e32 v89, v89
	v_add_f32_e32 v208, v86, v208
	v_exp_f32_e32 v90, v90
	v_add_f32_e32 v208, v87, v208
	v_exp_f32_e32 v91, v91
	v_add_f32_e32 v208, v88, v208
	v_exp_f32_e32 v92, v92
	v_add_f32_e32 v208, v89, v208
	v_exp_f32_e32 v93, v93
	v_add_f32_e32 v208, v90, v208
	v_exp_f32_e32 v94, v94
	v_add_f32_e32 v208, v91, v208
	v_exp_f32_e32 v95, v95
	v_add_f32_e32 v208, v92, v208
	v_add_f32_e32 v208, v93, v208
	v_add_f32_e32 v208, v94, v208
	v_add_f32_e32 v208, v95, v208
	v_cvt_pk_bf16_f32 v222, v80, v81
	v_cvt_pk_bf16_f32 v223, v82, v83
	v_cvt_pk_bf16_f32 v224, v84, v85
	v_cvt_pk_bf16_f32 v225, v86, v87
	v_cvt_pk_bf16_f32 v226, v88, v89
	v_cvt_pk_bf16_f32 v227, v90, v91
	v_cvt_pk_bf16_f32 v228, v92, v93
	v_cvt_pk_bf16_f32 v229, v94, v95
	ds_read_b64_tr_b16 v[82:83], v238 offset:35008
	ds_read_b64_tr_b16 v[84:85], v238 offset:37568
	ds_read_b64_tr_b16 v[86:87], v238 offset:39936
	ds_read_b64_tr_b16 v[88:89], v238 offset:42496
	ds_read_b64_tr_b16 v[90:91], v238 offset:40000
	ds_read_b64_tr_b16 v[92:93], v238 offset:42560
	s_waitcnt lgkmcnt(10)
	v_mfma_f32_32x32x16_bf16 v[0:15], v[240:243], v[222:225], v[0:15]
	ds_read_b64_tr_b16 v[240:241], v238 offset:40064
	ds_read_b64_tr_b16 v[242:243], v238 offset:42624
	v_exp_f32_e32 v96, v96
	v_exp_f32_e32 v97, v97
	v_add_f32_e32 v208, v96, v208
	v_add_f32_e32 v208, v97, v208
	v_cvt_pk_bf16_f32 v230, v96, v97
	s_waitcnt lgkmcnt(10)
	v_mfma_f32_32x32x16_bf16 v[32:47], v[244:247], v[222:225], v[32:47]
	ds_read_b64_tr_b16 v[244:245], v238 offset:40128
	ds_read_b64_tr_b16 v[246:247], v238 offset:42688
	v_exp_f32_e32 v98, v98
	v_exp_f32_e32 v99, v99
	v_add_f32_e32 v208, v98, v208
	v_add_f32_e32 v208, v99, v208
	v_cvt_pk_bf16_f32 v231, v98, v99
	s_waitcnt lgkmcnt(10)
	v_mfma_f32_32x32x16_bf16 v[16:31], v[248:251], v[222:225], v[16:31]
	ds_read_b64_tr_b16 v[248:249], v238 offset:45056
	ds_read_b64_tr_b16 v[250:251], v238 offset:47616
	v_exp_f32_e32 v100, v100
	v_exp_f32_e32 v101, v101
	v_add_f32_e32 v208, v100, v208
	v_add_f32_e32 v208, v101, v208
	v_cvt_pk_bf16_f32 v232, v100, v101
	s_waitcnt lgkmcnt(10)
	v_mfma_f32_32x32x16_bf16 v[48:63], v[82:85], v[222:225], v[48:63]
	ds_read_b64_tr_b16 v[82:83], v238 offset:45120
	ds_read_b64_tr_b16 v[84:85], v238 offset:47680
	v_exp_f32_e32 v102, v102
	v_exp_f32_e32 v103, v103
	v_add_f32_e32 v208, v102, v208
	v_add_f32_e32 v208, v103, v208
	v_cvt_pk_bf16_f32 v233, v102, v103
	s_waitcnt lgkmcnt(10)
	v_mfma_f32_32x32x16_bf16 v[0:15], v[86:89], v[226:229], v[0:15]
	ds_read_b64_tr_b16 v[86:87], v238 offset:45184
	ds_read_b64_tr_b16 v[88:89], v238 offset:47744
	v_exp_f32_e32 v104, v104
	v_exp_f32_e32 v105, v105
	v_add_f32_e32 v208, v104, v208
	v_add_f32_e32 v208, v105, v208
	v_cvt_pk_bf16_f32 v234, v104, v105
	s_waitcnt lgkmcnt(10)
	v_mfma_f32_32x32x16_bf16 v[32:47], v[90:93], v[226:229], v[32:47]
	ds_read_b64_tr_b16 v[90:91], v238 offset:45248
	ds_read_b64_tr_b16 v[92:93], v238 offset:47808
	v_exp_f32_e32 v106, v106
	v_exp_f32_e32 v107, v107
	v_add_f32_e32 v208, v106, v208
	v_add_f32_e32 v208, v107, v208
	v_cvt_pk_bf16_f32 v235, v106, v107
	s_waitcnt lgkmcnt(10)
	v_mfma_f32_32x32x16_bf16 v[16:31], v[240:243], v[226:229], v[16:31]
	ds_read_b64_tr_b16 v[240:241], v238 offset:50176
	ds_read_b64_tr_b16 v[242:243], v238 offset:52736
	v_exp_f32_e32 v108, v108
	v_exp_f32_e32 v109, v109
	v_add_f32_e32 v208, v108, v208
	v_add_f32_e32 v208, v109, v208
	v_cvt_pk_bf16_f32 v236, v108, v109
	s_waitcnt lgkmcnt(10)
	v_mfma_f32_32x32x16_bf16 v[48:63], v[244:247], v[226:229], v[48:63]
	ds_read_b64_tr_b16 v[244:245], v238 offset:50240
	ds_read_b64_tr_b16 v[246:247], v238 offset:52800
	v_exp_f32_e32 v110, v110
	v_exp_f32_e32 v111, v111
	v_add_f32_e32 v208, v110, v208
	v_add_f32_e32 v208, v111, v208
	v_cvt_pk_bf16_f32 v237, v110, v111
	s_waitcnt lgkmcnt(10)
	v_mfma_f32_32x32x16_bf16 v[0:15], v[248:251], v[230:233], v[0:15]
	ds_read_b64_tr_b16 v[248:249], v238 offset:50304
	ds_read_b64_tr_b16 v[250:251], v238 offset:52864
	v_add_f32_e32 v197, v197, v208
	s_waitcnt lgkmcnt(10)
	v_mfma_f32_32x32x16_bf16 v[32:47], v[82:85], v[230:233], v[32:47]
	ds_read_b64_tr_b16 v[82:83], v238 offset:50368
	ds_read_b64_tr_b16 v[84:85], v238 offset:52928
	s_waitcnt lgkmcnt(10)
	v_mfma_f32_32x32x16_bf16 v[16:31], v[86:89], v[230:233], v[16:31]
	s_waitcnt lgkmcnt(8)
	v_mfma_f32_32x32x16_bf16 v[48:63], v[90:93], v[230:233], v[48:63]
	s_waitcnt lgkmcnt(6)
	v_mfma_f32_32x32x16_bf16 v[0:15], v[240:243], v[234:237], v[0:15]
	s_waitcnt lgkmcnt(4)
	v_mfma_f32_32x32x16_bf16 v[32:47], v[244:247], v[234:237], v[32:47]
	s_waitcnt lgkmcnt(2)
	v_mfma_f32_32x32x16_bf16 v[16:31], v[248:251], v[234:237], v[16:31]
	s_waitcnt lgkmcnt(0)
	v_mfma_f32_32x32x16_bf16 v[48:63], v[82:85], v[234:237], v[48:63]
	s_branch .LBB0_211
